# v16 with the next-row wait placed in front of the row-statistics store (the wait then only covers loads)
# baseline (speedup 1.0000x reference)
; DI void lnmod_phase(const Args& A, LAS unsigned char* lds, int tid, int bid, int G, bool init, int l_norm, int i_norm, int l_mod, int i_mod, bool want_dt, int nrows, bool ctx_partial, const float* gprev, const float* bprev) {
;     ...
;             float s = 0.f, s2 = 0.f;
; #pragma unroll
;             for (int j = 0; j < 4; ++j) { s += (v[j].x + v[j].y) + (v[j].z + v[j].w); s2 += (v[j].x * v[j].x + v[j].y * v[j].y) + (v[j].z * v[j].z + v[j].w * v[j].w); }
;             wave_sum2(s, s2);
;             const float mean = s * (1.f / DM);
;             const float rstd = 1.0f / sqrtf(fmaxf(s2 * (1.f / DM) - mean * mean, 0.f) + 1e-5f);
; #pragma unroll
;             for (int j = 0; j < 4; ++j) v[j] = v[j] - mean;
;             if (l_mod >= 0 && lane == 0) STAT[row] = (f32x2){mean, rstd};
.LBB0_209:
	s_or_b64 exec, exec, s[6:7]
	s_andn2_b64 vcc, exec, s[8:9]
	s_cbranch_vccnz .Llnl1_bypass
	v_pk_add_f32 v[110:111], v[106:107], v[90:91]
	v_mul_f32_e32 v99, v91, v91
	v_add_f32_e32 v87, v110, v111
	v_add_f32_e32 v109, 0, v87
	v_mul_f32_e32 v87, v106, v106
	v_fmac_f32_e32 v87, v90, v90
	v_fmac_f32_e32 v99, v107, v107
	v_add_f32_e32 v87, v87, v99
	v_mul_f32_e32 v99, v102, v102
	v_mul_f32_e32 v101, v93, v93
	v_pk_add_f32 v[110:111], v[102:103], v[92:93]
	v_fmac_f32_e32 v99, v92, v92
	v_fmac_f32_e32 v101, v103, v103
	v_pk_add_f32 v[110:111], v[110:111], v[110:111] op_sel_hi:[0,1]
	v_add_f32_e32 v99, v99, v101
	v_add_f32_e32 v87, v87, v99
	v_mul_f32_e32 v99, v97, v97
	v_mul_f32_e32 v110, v95, v95
	v_add_f32_e32 v101, v96, v97
	v_add_f32_e32 v105, v94, v95
	v_fmac_f32_e32 v99, v96, v96
	v_fmac_f32_e32 v110, v94, v94
	v_add_f32_e32 v99, v99, v110
	v_pk_add_f32 v[112:113], v[100:101], v[104:105]
	v_mul_f32_e32 v101, v104, v104
	v_mul_f32_e32 v105, v108, v108
	v_add_f32_e32 v87, v99, v87
	v_mov_b32_e32 v99, v111
	v_fmac_f32_e32 v101, v100, v100
	v_fmac_f32_e32 v105, v98, v98
	v_pk_add_f32 v[110:111], v[98:99], v[108:109]
	v_add_f32_e32 v101, v101, v105
	v_pk_add_f32 v[110:111], v[112:113], v[110:111]
	v_add_f32_e32 v87, v101, v87
	v_and_b32_e32 v101, 64, v210
	v_add_f32_e32 v99, v110, v111
	v_add_u32_e32 v110, 64, v101
	v_xor_b32_e32 v101, 1, v210
	v_cmp_lt_i32_e32 vcc, v101, v110
	s_mov_b32 s6, 0x3a800000
	s_nop 0
	v_cndmask_b32_e32 v101, v210, v101, vcc
	v_lshlrev_b32_e32 v114, 2, v101
	s_nop 1
	v_mov_b32_dpp v101, v99 quad_perm:[1,0,3,2] row_mask:0xf bank_mask:0xf
	v_mov_b32_dpp v105, v87 quad_perm:[1,0,3,2] row_mask:0xf bank_mask:0xf
	s_waitcnt lgkmcnt(1)
	v_add_f32_e32 v99, v99, v101
	v_xor_b32_e32 v101, 2, v210
	v_cmp_lt_i32_e32 vcc, v101, v110
	s_waitcnt lgkmcnt(0)
	v_add_f32_e32 v87, v87, v105
	v_cndmask_b32_e32 v101, v210, v101, vcc
	v_lshlrev_b32_e32 v111, 2, v101
	s_nop 1
	v_mov_b32_dpp v101, v99 quad_perm:[2,3,0,1] row_mask:0xf bank_mask:0xf
	v_mov_b32_dpp v105, v87 quad_perm:[2,3,0,1] row_mask:0xf bank_mask:0xf
	s_waitcnt lgkmcnt(1)
	v_add_f32_e32 v99, v99, v101
	v_xor_b32_e32 v101, 4, v210
	v_cmp_lt_i32_e32 vcc, v101, v110
	s_waitcnt lgkmcnt(0)
	v_add_f32_e32 v87, v87, v105
	v_cndmask_b32_e32 v101, v210, v101, vcc
	v_lshlrev_b32_e32 v109, 2, v101
	s_nop 1
	v_mov_b32_dpp v101, v99 row_half_mirror row_mask:0xf bank_mask:0xf
	v_mov_b32_dpp v105, v87 row_half_mirror row_mask:0xf bank_mask:0xf
	s_waitcnt lgkmcnt(1)
	v_add_f32_e32 v99, v99, v101
	v_xor_b32_e32 v101, 8, v210
	v_cmp_lt_i32_e32 vcc, v101, v110
	s_waitcnt lgkmcnt(0)
	v_add_f32_e32 v87, v87, v105
	v_cndmask_b32_e32 v101, v210, v101, vcc
	v_lshlrev_b32_e32 v105, 2, v101
	s_nop 1
	v_mov_b32_dpp v101, v99 row_mirror row_mask:0xf bank_mask:0xf
	v_mov_b32_dpp v112, v87 row_mirror row_mask:0xf bank_mask:0xf
	s_waitcnt lgkmcnt(1)
	v_add_f32_e32 v99, v99, v101
	v_xor_b32_e32 v101, 16, v210
	v_cmp_lt_i32_e32 vcc, v101, v110
	s_waitcnt lgkmcnt(0)
	v_add_f32_e32 v87, v87, v112
	v_cndmask_b32_e32 v101, v210, v101, vcc
	v_lshlrev_b32_e32 v101, 2, v101
	v_mov_b32_e32 v112, v99
	v_mov_b32_e32 v113, v87
	s_nop 1
	v_permlane16_swap_b32_e32 v99, v112
	v_permlane16_swap_b32_e32 v87, v113
	s_waitcnt lgkmcnt(1)
	v_add_f32_e32 v112, v99, v112
	v_xor_b32_e32 v99, 32, v210
	v_cmp_lt_i32_e32 vcc, v99, v110
	s_waitcnt lgkmcnt(0)
	v_add_f32_e32 v87, v87, v113
	v_cndmask_b32_e32 v99, v210, v99, vcc
	v_lshlrev_b32_e32 v99, 2, v99
	v_mov_b32_e32 v110, v112
	v_mov_b32_e32 v113, v87
	s_nop 1
	v_permlane32_swap_b32_e32 v112, v110
	v_permlane32_swap_b32_e32 v87, v113
	s_waitcnt lgkmcnt(1)
	v_add_f32_e32 v110, v112, v110
	v_mul_f32_e32 v112, 0x3a800000, v110
	s_waitcnt lgkmcnt(0)
	v_add_f32_e32 v87, v87, v113
	v_mul_f32_e32 v110, v112, v112
	v_fma_f32 v87, v87, s6, -v110
	v_max_f32_e32 v87, 0, v87
	v_add_f32_e32 v87, 0x3727c5ac, v87
	v_mul_f32_e32 v110, 0x4f800000, v87
	v_cmp_gt_f32_e32 vcc, s65, v87
	s_nop 1
	v_cndmask_b32_e32 v87, v87, v110, vcc
	v_sqrt_f32_e32 v110, v87
	s_nop 0
	v_add_u32_e32 v113, -1, v110
	v_fma_f32 v115, -v113, v110, v87
	v_cmp_ge_f32_e64 s[6:7], 0, v115
	v_add_u32_e32 v115, 1, v110
	s_nop 0
	v_cndmask_b32_e64 v113, v110, v113, s[6:7]
	v_fma_f32 v110, -v115, v110, v87
	v_cmp_lt_f32_e64 s[6:7], 0, v110
	s_nop 1
	v_cndmask_b32_e64 v110, v113, v115, s[6:7]
	v_mul_f32_e32 v113, 0x37800000, v110
	v_cndmask_b32_e32 v110, v110, v113, vcc
	v_cmp_class_f32_e32 vcc, v87, v208
	s_nop 1
	v_cndmask_b32_e32 v87, v110, v87, vcc
	v_div_scale_f32 v110, s[6:7], v87, v87, 1.0
	v_rcp_f32_e32 v113, v110
	s_nop 0
	v_fma_f32 v115, -v110, v113, 1.0
	v_fmac_f32_e32 v113, v115, v113
	v_div_scale_f32 v115, vcc, 1.0, v87, 1.0
	v_mul_f32_e32 v118, v115, v113
	v_fma_f32 v119, -v110, v118, v115
	v_fmac_f32_e32 v118, v119, v113
	v_fma_f32 v110, -v110, v118, v115
	v_div_fmas_f32 v110, v110, v113, v118
	v_div_fixup_f32 v110, v110, v87, 1.0
	s_waitcnt vmcnt(0)
	v_mov_b32_e32 v172, v78
	v_mov_b32_e32 v173, v79
	v_mov_b32_e32 v174, v80
	v_mov_b32_e32 v175, v81
	v_mov_b32_e32 v176, v82
	v_mov_b32_e32 v177, v83
	v_mov_b32_e32 v178, v84
	v_mov_b32_e32 v179, v85
	s_and_saveexec_b64 s[6:7], s[20:21]
	s_cbranch_execz .LBB0_212
	v_readlane_b32 s36, v253, 23
	v_readlane_b32 s38, v253, 25
	v_readlane_b32 s39, v253, 26
	v_mov_b32_e32 v113, v110
	v_readlane_b32 s37, v253, 24
	v_lshl_add_u64 v[118:119], s[38:39], 0, v[74:75]
	global_store_dwordx2 v[118:119], v[112:113], off

; DI void lnmod_phase(const Args& A, LAS unsigned char* lds, int tid, int bid, int G, bool init, int l_norm, int i_norm, int l_mod, int i_mod, bool want_dt, int nrows, bool ctx_partial, const float* gprev, const float* bprev) {
;     ...
;             float s = 0.f, s2 = 0.f;
; #pragma unroll
;             for (int j = 0; j < 4; ++j) { s += (v[j].x + v[j].y) + (v[j].z + v[j].w); s2 += (v[j].x * v[j].x + v[j].y * v[j].y) + (v[j].z * v[j].z + v[j].w * v[j].w); }
;             wave_sum2(s, s2);
;             const float mean = s * (1.f / DM);
;             const float rstd = 1.0f / sqrtf(fmaxf(s2 * (1.f / DM) - mean * mean, 0.f) + 1e-5f);
; #pragma unroll
;             for (int j = 0; j < 4; ++j) v[j] = v[j] - mean;
;             if (l_mod >= 0 && lane == 0) STAT[row] = (f32x2){mean, rstd};
.LBB0_284:
	s_or_b64 exec, exec, s[4:5]
	s_andn2_b64 vcc, exec, s[2:3]
	s_cbranch_vccnz .Llnl3_bypass
	v_pk_add_f32 v[108:109], v[104:105], v[88:89]
	v_mul_f32_e32 v99, v89, v89
	v_add_f32_e32 v97, v108, v109
	v_add_f32_e32 v107, 0, v97
	v_mul_f32_e32 v97, v104, v104
	v_fmac_f32_e32 v97, v88, v88
	v_fmac_f32_e32 v99, v105, v105
	v_add_f32_e32 v97, v97, v99
	v_pk_add_f32 v[108:109], v[100:101], v[90:91]
	v_mul_f32_e32 v99, v100, v100
	v_mul_f32_e32 v103, v91, v91
	v_pk_add_f32 v[108:109], v[108:109], v[108:109] op_sel_hi:[0,1]
	v_fmac_f32_e32 v99, v90, v90
	v_fmac_f32_e32 v103, v101, v101
	v_add_f32_e32 v99, v99, v103
	v_mul_f32_e32 v108, v95, v95
	v_mul_f32_e32 v110, v93, v93
	v_add_f32_e32 v97, v97, v99
	v_add_f32_e32 v99, v94, v95
	v_add_f32_e32 v103, v92, v93
	v_fmac_f32_e32 v108, v94, v94
	v_fmac_f32_e32 v110, v92, v92
	v_add_f32_e32 v108, v108, v110
	v_pk_add_f32 v[110:111], v[98:99], v[102:103]
	v_mul_f32_e32 v99, v102, v102
	v_mul_f32_e32 v103, v106, v106
	v_fmac_f32_e32 v99, v98, v98
	v_fmac_f32_e32 v103, v96, v96
	v_add_f32_e32 v112, v108, v97
	v_mov_b32_e32 v97, v109
	v_add_f32_e32 v99, v99, v103
	v_and_b32_e32 v103, 64, v210
	v_pk_add_f32 v[108:109], v[96:97], v[106:107]
	v_add_u32_e32 v103, 64, v103
	v_xor_b32_e32 v107, 1, v210
	v_cmp_lt_i32_e32 vcc, v107, v103
	v_pk_add_f32 v[108:109], v[110:111], v[108:109]
	v_add_f32_e32 v99, v99, v112
	v_cndmask_b32_e32 v107, v210, v107, vcc
	v_add_f32_e32 v97, v108, v109
	v_lshlrev_b32_e32 v107, 2, v107
	s_nop 1
	v_mov_b32_dpp v108, v97 quad_perm:[1,0,3,2] row_mask:0xf bank_mask:0xf
	v_mov_b32_dpp v107, v99 quad_perm:[1,0,3,2] row_mask:0xf bank_mask:0xf
	s_mov_b32 s4, 0x3a800000
	s_waitcnt lgkmcnt(1)
	v_add_f32_e32 v97, v97, v108
	s_waitcnt lgkmcnt(0)
	v_add_f32_e32 v99, v99, v107
	v_xor_b32_e32 v107, 2, v210
	v_cmp_lt_i32_e32 vcc, v107, v103
	s_nop 1
	v_cndmask_b32_e32 v107, v210, v107, vcc
	v_lshlrev_b32_e32 v107, 2, v107
	s_nop 1
	v_mov_b32_dpp v108, v97 quad_perm:[2,3,0,1] row_mask:0xf bank_mask:0xf
	v_mov_b32_dpp v107, v99 quad_perm:[2,3,0,1] row_mask:0xf bank_mask:0xf
	s_waitcnt lgkmcnt(1)
	v_add_f32_e32 v97, v97, v108
	s_waitcnt lgkmcnt(0)
	v_add_f32_e32 v99, v99, v107
	v_xor_b32_e32 v107, 4, v210
	v_cmp_lt_i32_e32 vcc, v107, v103
	s_nop 1
	v_cndmask_b32_e32 v107, v210, v107, vcc
	v_lshlrev_b32_e32 v107, 2, v107
	s_nop 1
	v_mov_b32_dpp v108, v97 row_half_mirror row_mask:0xf bank_mask:0xf
	v_mov_b32_dpp v107, v99 row_half_mirror row_mask:0xf bank_mask:0xf
	s_waitcnt lgkmcnt(1)
	v_add_f32_e32 v97, v97, v108
	s_waitcnt lgkmcnt(0)
	v_add_f32_e32 v99, v99, v107
	v_xor_b32_e32 v107, 8, v210
	v_cmp_lt_i32_e32 vcc, v107, v103
	s_nop 1
	v_cndmask_b32_e32 v107, v210, v107, vcc
	v_lshlrev_b32_e32 v107, 2, v107
	s_nop 1
	v_mov_b32_dpp v108, v97 row_mirror row_mask:0xf bank_mask:0xf
	v_mov_b32_dpp v107, v99 row_mirror row_mask:0xf bank_mask:0xf
	s_waitcnt lgkmcnt(1)
	v_add_f32_e32 v97, v97, v108
	s_waitcnt lgkmcnt(0)
	v_add_f32_e32 v99, v99, v107
	v_xor_b32_e32 v107, 16, v210
	v_cmp_lt_i32_e32 vcc, v107, v103
	s_nop 1
	v_cndmask_b32_e32 v107, v210, v107, vcc
	v_lshlrev_b32_e32 v107, 2, v107
	v_mov_b32_e32 v108, v97
	v_mov_b32_e32 v107, v99
	s_nop 1
	v_permlane16_swap_b32_e32 v97, v108
	v_permlane16_swap_b32_e32 v99, v107
	s_waitcnt lgkmcnt(1)
	v_add_f32_e32 v97, v97, v108
	s_waitcnt lgkmcnt(0)
	v_add_f32_e32 v99, v99, v107
	v_xor_b32_e32 v107, 32, v210
	v_cmp_lt_i32_e32 vcc, v107, v103
	s_nop 1
	v_cndmask_b32_e32 v103, v210, v107, vcc
	v_lshlrev_b32_e32 v103, 2, v103
	v_mov_b32_e32 v107, v97
	v_mov_b32_e32 v103, v99
	s_nop 1
	v_permlane32_swap_b32_e32 v97, v107
	v_permlane32_swap_b32_e32 v99, v103
	s_waitcnt lgkmcnt(1)
	v_add_f32_e32 v97, v97, v107
	v_mul_f32_e32 v110, 0x3a800000, v97
	s_waitcnt lgkmcnt(0)
	v_add_f32_e32 v99, v99, v103
	v_mul_f32_e32 v97, v110, v110
	v_fma_f32 v97, v99, s4, -v97
	v_max_f32_e32 v97, 0, v97
	v_add_f32_e32 v97, 0x3727c5ac, v97
	v_mul_f32_e32 v99, 0x4f800000, v97
	v_cmp_gt_f32_e32 vcc, s65, v97
	s_nop 1
	v_cndmask_b32_e32 v97, v97, v99, vcc
	v_sqrt_f32_e32 v99, v97
	s_nop 0
	v_add_u32_e32 v103, -1, v99
	v_fma_f32 v107, -v103, v99, v97
	v_cmp_ge_f32_e64 s[4:5], 0, v107
	v_add_u32_e32 v107, 1, v99
	s_nop 0
	v_cndmask_b32_e64 v103, v99, v103, s[4:5]
	v_fma_f32 v99, -v107, v99, v97
	v_cmp_lt_f32_e64 s[4:5], 0, v99
	s_nop 1
	v_cndmask_b32_e64 v99, v103, v107, s[4:5]
	v_mul_f32_e32 v103, 0x37800000, v99
	v_cndmask_b32_e32 v99, v99, v103, vcc
	v_cmp_class_f32_e32 vcc, v97, v208
	s_nop 1
	v_cndmask_b32_e32 v97, v99, v97, vcc
	v_div_scale_f32 v99, s[4:5], v97, v97, 1.0
	v_rcp_f32_e32 v103, v99
	s_nop 0
	v_fma_f32 v107, -v99, v103, 1.0
	v_fmac_f32_e32 v103, v107, v103
	v_div_scale_f32 v107, vcc, 1.0, v97, 1.0
	v_mul_f32_e32 v108, v107, v103
	v_fma_f32 v109, -v99, v108, v107
	v_fmac_f32_e32 v108, v109, v103
	v_fma_f32 v99, -v99, v108, v107
	v_div_fmas_f32 v99, v99, v103, v108
	v_div_fixup_f32 v108, v99, v97, 1.0
	s_waitcnt vmcnt(0)
	v_mov_b32_e32 v124, v76
	v_mov_b32_e32 v125, v77
	v_mov_b32_e32 v126, v78
	v_mov_b32_e32 v127, v79
	v_mov_b32_e32 v128, v80
	v_mov_b32_e32 v129, v81
	v_mov_b32_e32 v130, v82
	v_mov_b32_e32 v131, v83
	s_and_saveexec_b64 s[4:5], s[14:15]
	s_cbranch_execz .LBB0_287
	v_readlane_b32 s24, v253, 23
	v_readlane_b32 s26, v253, 25
	v_readlane_b32 s27, v253, 26
	v_mov_b32_e32 v111, v108
	v_readlane_b32 s25, v253, 24
	v_lshl_add_u64 v[112:113], s[26:27], 0, v[74:75]
	global_store_dwordx2 v[112:113], v[110:111], off
